# diff attention loop: K fragments 8 deep in V fragment registers, V reads behind K reads, K/V global loads issued behind restaging, conflict-free K layout
# speedup vs baseline: 1.0152x; 1.0049x over previous
.LBB0_147:
	s_bitcmp1_b32 s1, 0
	s_cselect_b32 s0, 0x9000, 0
	s_andn2_b32 s8, 1, s1
	v_add3_u32 v247, s0, v192, v233
	s_mul_i32 s8, s8, 0x9000
	ds_read_b128 v[156:159], v247
	ds_read_b128 v[152:155], v247 offset:128
	ds_read_b128 v[148:151], v247 offset:64
	ds_read_b128 v[144:147], v247 offset:192
	ds_read_b128 v[140:143], v247 offset:1280
	ds_read_b128 v[136:139], v247 offset:1408
	ds_read_b128 v[132:135], v247 offset:1344
	ds_read_b128 v[128:131], v247 offset:1472
	v_add_u32_e32 v160, s0, v235
	v_add3_u32 v160, v160, v236, v237
	v_xor_b32_e32 v161, 32, v238
	v_add_u32_e32 v245, v160, v161
	v_xor_b32_e32 v161, 64, v238
	v_add_u32_e32 v244, v160, v161
	v_xor_b32_e32 v161, 0x60, v238
	v_add_u32_e32 v243, v160, v161
	v_xor_b32_e32 v161, 0x80, v238
	v_add_u32_e32 v242, v160, v161
	v_xor_b32_e32 v161, 0xa0, v238
	v_add_u32_e32 v241, v160, v161
	v_xor_b32_e32 v161, 0xc0, v238
	v_add_u32_e32 v240, v160, v161
	v_xor_b32_e32 v161, 0xe0, v238
	v_add_u32_e32 v246, v160, v238
	v_add_u32_e32 v239, v160, v161
	v_add3_u32 v160, s8, v205, v207
	v_add3_u32 v161, s8, v227, v228
	s_waitcnt vmcnt(3)
	ds_write_b128 v160, v[16:19]
	v_add_u32_e32 v160, s8, v209
	s_waitcnt vmcnt(2)
	ds_write_b128 v161, v[20:23]
	v_add3_u32 v160, v160, v211, v229
	v_add_u32_e32 v161, s8, v230
	s_waitcnt vmcnt(1)
	ds_write_b128 v160, v[24:27] offset:20480
	v_add3_u32 v161, v161, v231, v232
	s_add_i32 s8, s1, 3
	s_add_i32 s0, s1, 2
	s_waitcnt vmcnt(0)
	ds_write_b128 v161, v[28:31] offset:20480
	s_min_u32 s8, s8, s83
	s_min_u32 s0, s0, s83
	s_lshl_b32 s8, s8, 6
	s_lshl_b32 s0, s0, 6
	v_add_u32_e32 v16, s8, v204
	v_add_u32_e32 v164, s8, v206
	v_add_u32_e32 v184, s0, v208
	v_add_u32_e32 v28, s0, v210
	v_ashrrev_i32_e32 v17, 31, v16
	v_ashrrev_i32_e32 v165, 31, v164
	v_ashrrev_i32_e32 v185, 31, v184
	v_ashrrev_i32_e32 v29, 31, v28
	v_lshlrev_b64 v[16:17], 11, v[16:17]
	v_lshlrev_b64 v[20:21], 11, v[164:165]
	v_lshlrev_b64 v[24:25], 11, v[184:185]
	v_lshlrev_b64 v[28:29], 11, v[28:29]
	v_lshl_add_u64 v[16:17], v[212:213], 0, v[16:17]
	v_lshl_add_u64 v[20:21], v[214:215], 0, v[20:21]
	v_lshl_add_u64 v[24:25], v[216:217], 0, v[24:25]
	v_lshl_add_u64 v[28:29], v[218:219], 0, v[28:29]
	global_load_dwordx4 v[16:19], v[16:17], off
	global_load_dwordx4 v[20:23], v[20:21], off
	global_load_dwordx4 v[24:27], v[24:25], off offset:1024
	global_load_dwordx4 v[28:31], v[28:29], off offset:1024
	s_waitcnt lgkmcnt(11)
	v_mfma_f32_16x16x32_bf16 v[188:191], v[156:159], v[0:3], v[40:43]
	ds_read_b128 v[156:159], v247 offset:10240
	s_waitcnt lgkmcnt(11)
	v_mfma_f32_16x16x32_bf16 v[160:163], v[152:155], v[8:11], v[44:47]
	ds_read_b128 v[152:155], v247 offset:10368
	s_waitcnt lgkmcnt(11)
	v_mfma_f32_16x16x32_bf16 v[188:191], v[148:151], v[4:7], v[188:191]
	ds_read_b128 v[148:151], v247 offset:10304
	s_waitcnt lgkmcnt(11)
	v_mfma_f32_16x16x32_bf16 v[160:163], v[144:147], v[12:15], v[160:163]
	ds_read_b128 v[144:147], v247 offset:10432
	s_waitcnt lgkmcnt(11)
	v_mfma_f32_16x16x32_bf16 v[184:187], v[140:143], v[0:3], v[40:43]
	ds_read_b128 v[140:143], v247 offset:11520
	s_waitcnt lgkmcnt(11)
	v_mfma_f32_16x16x32_bf16 v[168:171], v[136:139], v[8:11], v[44:47]
	ds_read_b128 v[136:139], v247 offset:11648
	s_waitcnt lgkmcnt(11)
	v_mfma_f32_16x16x32_bf16 v[184:187], v[132:135], v[4:7], v[184:187]
	ds_read_b128 v[132:135], v247 offset:11584
	s_waitcnt lgkmcnt(11)
	v_mfma_f32_16x16x32_bf16 v[168:171], v[128:131], v[12:15], v[168:171]
	ds_read_b128 v[128:131], v247 offset:11712
	s_waitcnt lgkmcnt(7)
	v_mfma_f32_16x16x32_bf16 v[180:183], v[156:159], v[0:3], v[40:43]
	ds_read_b64_tr_b16 v[156:157], v246 offset:20480
	ds_read_b64_tr_b16 v[158:159], v246 offset:21504
	s_waitcnt lgkmcnt(8)
	v_mfma_f32_16x16x32_bf16 v[164:167], v[152:155], v[8:11], v[44:47]
	ds_read_b64_tr_b16 v[152:153], v245 offset:20480
	ds_read_b64_tr_b16 v[154:155], v245 offset:21504
	s_waitcnt lgkmcnt(9)
	v_mfma_f32_16x16x32_bf16 v[180:183], v[148:151], v[4:7], v[180:183]
	ds_read_b64_tr_b16 v[148:149], v244 offset:20480
	ds_read_b64_tr_b16 v[150:151], v244 offset:21504
	s_waitcnt lgkmcnt(10)
	v_mfma_f32_16x16x32_bf16 v[164:167], v[144:147], v[12:15], v[164:167]
	ds_read_b64_tr_b16 v[144:145], v243 offset:20480
	ds_read_b64_tr_b16 v[146:147], v243 offset:21504
	s_waitcnt lgkmcnt(11)
	v_mfma_f32_16x16x32_bf16 v[172:175], v[140:143], v[0:3], v[40:43]
	ds_read_b64_tr_b16 v[140:141], v242 offset:20480
	ds_read_b64_tr_b16 v[142:143], v242 offset:21504
	s_waitcnt lgkmcnt(12)
	v_mfma_f32_16x16x32_bf16 v[176:179], v[136:139], v[8:11], v[44:47]
	ds_read_b64_tr_b16 v[136:137], v241 offset:20480
	ds_read_b64_tr_b16 v[138:139], v241 offset:21504
	s_waitcnt lgkmcnt(13)
	v_mfma_f32_16x16x32_bf16 v[172:175], v[132:135], v[4:7], v[172:175]
	ds_read_b64_tr_b16 v[132:133], v240 offset:20480
	ds_read_b64_tr_b16 v[134:135], v240 offset:21504
	s_waitcnt lgkmcnt(14)
	v_mfma_f32_16x16x32_bf16 v[176:179], v[128:131], v[12:15], v[176:179]
	ds_read_b64_tr_b16 v[128:129], v239 offset:20480
	ds_read_b64_tr_b16 v[130:131], v239 offset:21504
	s_add_i32 s8, s1, 1
	s_cmp_ge_u32 s8, s82
	s_cbranch_scc1 .LBB0_153
	s_cmp_lg_u32 s1, 0
	s_cselect_b64 s[0:1], -1, 0
	s_and_b32 s9, s8, 3
	s_cmp_lg_u32 s9, 0
	s_cselect_b64 s[14:15], -1, 0
	s_and_b64 s[0:1], s[0:1], s[14:15]
	s_and_b64 vcc, exec, s[0:1]
	s_cbranch_vccnz .LBB0_153
	v_max_f32_e32 v194, v189, v189
	v_max_f32_e32 v195, v188, v188
	v_max_f32_e32 v194, v195, v194
	v_max3_f32 v194, v194, v190, v191
	v_max3_f32 v194, v194, v184, v185
	v_max3_f32 v194, v194, v186, v187
	v_max3_f32 v194, v194, v180, v181
	v_max3_f32 v194, v194, v182, v183
	v_max3_f32 v194, v194, v172, v173
	v_max3_f32 v194, v194, v174, v175
	v_mov_b32_e32 v195, v194
	s_nop 1
	v_permlane16_swap_b32_e32 v194, v195
	v_max_f32_e32 v195, v195, v195
	v_max_f32_e32 v194, v194, v194
	v_max_f32_e32 v194, v194, v195
	v_mov_b32_e32 v195, v194
	s_nop 1
	v_permlane32_swap_b32_e32 v194, v195
	v_max_f32_e32 v195, v195, v195
	v_max_f32_e32 v194, v194, v194
	v_max_f32_e32 v247, v194, v195
	v_cmp_lt_f32_e32 vcc, s44, v247
	s_cbranch_vccz .LBB0_151
	s_nop 0
	v_cndmask_b32_e32 v247, 0, v247, vcc
	v_exp_f32_e64 v194, -v247
	v_lshlrev_b32_e32 v196, 16, v72
	v_and_b32_e32 v197, 0xffff0000, v72
	v_sub_f32_e32 v191, v191, v247
	v_pk_mul_f32 v[196:197], v[194:195], v[196:197] op_sel_hi:[0,1]
	v_cvt_pk_bf16_f32 v72, v196, v197
	v_lshlrev_b32_e32 v196, 16, v73
	v_and_b32_e32 v197, 0xffff0000, v73
	v_pk_mul_f32 v[196:197], v[194:195], v[196:197] op_sel_hi:[0,1]
	v_cvt_pk_bf16_f32 v73, v196, v197
	v_lshlrev_b32_e32 v196, 16, v74
	v_and_b32_e32 v197, 0xffff0000, v74
	v_pk_mul_f32 v[196:197], v[194:195], v[196:197] op_sel_hi:[0,1]
	v_cvt_pk_bf16_f32 v74, v196, v197
	v_lshlrev_b32_e32 v196, 16, v75
	v_and_b32_e32 v197, 0xffff0000, v75
	v_pk_mul_f32 v[196:197], v[194:195], v[196:197] op_sel_hi:[0,1]
	v_cvt_pk_bf16_f32 v75, v196, v197
	v_lshlrev_b32_e32 v196, 16, v56
	v_and_b32_e32 v197, 0xffff0000, v56
	v_pk_mul_f32 v[196:197], v[194:195], v[196:197] op_sel_hi:[0,1]
	v_cvt_pk_bf16_f32 v56, v196, v197
	v_lshlrev_b32_e32 v196, 16, v57
	v_and_b32_e32 v197, 0xffff0000, v57
	v_pk_mul_f32 v[196:197], v[194:195], v[196:197] op_sel_hi:[0,1]
	v_cvt_pk_bf16_f32 v57, v196, v197
	v_lshlrev_b32_e32 v196, 16, v58
	v_and_b32_e32 v197, 0xffff0000, v58
	v_pk_mul_f32 v[196:197], v[194:195], v[196:197] op_sel_hi:[0,1]
	v_cvt_pk_bf16_f32 v58, v196, v197
	v_lshlrev_b32_e32 v196, 16, v59
	v_and_b32_e32 v197, 0xffff0000, v59
	v_pk_mul_f32 v[110:111], v[110:111], v[194:195] op_sel_hi:[1,0]
	v_pk_mul_f32 v[108:109], v[108:109], v[194:195] op_sel_hi:[1,0]
	v_pk_mul_f32 v[122:123], v[122:123], v[194:195] op_sel_hi:[1,0]
	v_pk_mul_f32 v[120:121], v[120:121], v[194:195] op_sel_hi:[1,0]
	v_pk_mul_f32 v[114:115], v[114:115], v[194:195] op_sel_hi:[1,0]
	v_pk_mul_f32 v[112:113], v[112:113], v[194:195] op_sel_hi:[1,0]
	v_pk_mul_f32 v[98:99], v[98:99], v[194:195] op_sel_hi:[1,0]
	v_pk_mul_f32 v[96:97], v[96:97], v[194:195] op_sel_hi:[1,0]
	v_pk_mul_f32 v[86:87], v[86:87], v[194:195] op_sel_hi:[1,0]
	v_pk_mul_f32 v[84:85], v[84:85], v[194:195] op_sel_hi:[1,0]
	v_pk_mul_f32 v[70:71], v[70:71], v[194:195] op_sel_hi:[1,0]
	v_pk_mul_f32 v[68:69], v[68:69], v[194:195] op_sel_hi:[1,0]
	v_pk_mul_f32 v[62:63], v[62:63], v[194:195] op_sel_hi:[1,0]
	v_pk_mul_f32 v[60:61], v[60:61], v[194:195] op_sel_hi:[1,0]
	v_pk_mul_f32 v[50:51], v[50:51], v[194:195] op_sel_hi:[1,0]
	v_pk_mul_f32 v[48:49], v[48:49], v[194:195] op_sel_hi:[1,0]
	v_pk_mul_f32 v[34:35], v[34:35], v[194:195] op_sel_hi:[1,0]
	v_pk_mul_f32 v[32:33], v[32:33], v[194:195] op_sel_hi:[1,0]
	v_pk_mul_f32 v[194:195], v[194:195], v[196:197] op_sel_hi:[0,1]
	v_sub_f32_e32 v190, v190, v247
	v_sub_f32_e32 v189, v189, v247
	v_sub_f32_e32 v188, v188, v247
	v_sub_f32_e32 v187, v187, v247
	v_sub_f32_e32 v186, v186, v247
	v_sub_f32_e32 v185, v185, v247
	v_sub_f32_e32 v184, v184, v247
	v_sub_f32_e32 v183, v183, v247
	v_sub_f32_e32 v182, v182, v247
	v_sub_f32_e32 v181, v181, v247
	v_sub_f32_e32 v180, v180, v247
	v_sub_f32_e32 v175, v175, v247
	v_sub_f32_e32 v174, v174, v247
	v_sub_f32_e32 v173, v173, v247
	v_sub_f32_e32 v172, v172, v247
	v_cvt_pk_bf16_f32 v59, v194, v195
	v_sub_f32_e32 v43, v43, v247
	v_sub_f32_e32 v42, v42, v247
	v_sub_f32_e32 v41, v41, v247
	v_sub_f32_e32 v40, v40, v247

.LBB0_153:
	s_waitcnt lgkmcnt(14)
	v_mfma_f32_16x16x32_bf16 v[120:123], v[156:159], v[72:75], v[120:123]
	v_exp_f32_e32 v188, v188
	v_exp_f32_e32 v189, v189
	v_mfma_f32_16x16x32_bf16 v[124:127], v[156:159], v[100:103], v[124:127]
	ds_read_b64_tr_b16 v[156:157], v246 offset:28672
	ds_read_b64_tr_b16 v[158:159], v246 offset:29696
	s_waitcnt lgkmcnt(14)
	v_mfma_f32_16x16x32_bf16 v[112:115], v[152:155], v[72:75], v[112:115]
	v_exp_f32_e32 v190, v190
	v_exp_f32_e32 v191, v191
	v_mfma_f32_16x16x32_bf16 v[116:119], v[152:155], v[100:103], v[116:119]
	ds_read_b64_tr_b16 v[152:153], v245 offset:28672
	ds_read_b64_tr_b16 v[154:155], v245 offset:29696
	s_waitcnt lgkmcnt(14)
	v_mfma_f32_16x16x32_bf16 v[96:99], v[148:151], v[72:75], v[96:99]
	v_exp_f32_e32 v184, v184
	v_exp_f32_e32 v185, v185
	v_mfma_f32_16x16x32_bf16 v[104:107], v[148:151], v[100:103], v[104:107]
	ds_read_b64_tr_b16 v[148:149], v244 offset:28672
	ds_read_b64_tr_b16 v[150:151], v244 offset:29696
	s_waitcnt lgkmcnt(14)
	v_mfma_f32_16x16x32_bf16 v[84:87], v[144:147], v[72:75], v[84:87]
	v_exp_f32_e32 v186, v186
	v_exp_f32_e32 v187, v187
	v_mfma_f32_16x16x32_bf16 v[88:91], v[144:147], v[100:103], v[88:91]
	ds_read_b64_tr_b16 v[144:145], v243 offset:28672
	ds_read_b64_tr_b16 v[146:147], v243 offset:29696
	s_waitcnt lgkmcnt(14)
	v_mfma_f32_16x16x32_bf16 v[68:71], v[140:143], v[72:75], v[68:71]
	v_exp_f32_e32 v194, v180
	v_exp_f32_e32 v195, v181
	v_mfma_f32_16x16x32_bf16 v[76:79], v[140:143], v[100:103], v[76:79]
	ds_read_b64_tr_b16 v[140:141], v242 offset:28672
	ds_read_b64_tr_b16 v[142:143], v242 offset:29696
	s_waitcnt lgkmcnt(14)
	v_mfma_f32_16x16x32_bf16 v[60:63], v[136:139], v[72:75], v[60:63]
	v_exp_f32_e32 v196, v182
	v_exp_f32_e32 v197, v183
	v_mfma_f32_16x16x32_bf16 v[64:67], v[136:139], v[100:103], v[64:67]
	ds_read_b64_tr_b16 v[136:137], v241 offset:28672
	ds_read_b64_tr_b16 v[138:139], v241 offset:29696
	s_waitcnt lgkmcnt(14)
	v_mfma_f32_16x16x32_bf16 v[48:51], v[132:135], v[72:75], v[48:51]
	v_exp_f32_e32 v172, v172
	v_exp_f32_e32 v173, v173
	v_mfma_f32_16x16x32_bf16 v[52:55], v[132:135], v[100:103], v[52:55]
	ds_read_b64_tr_b16 v[132:133], v240 offset:28672
	ds_read_b64_tr_b16 v[134:135], v240 offset:29696
	s_mov_b32 s30, s28
	s_mov_b32 s31, s28
	s_waitcnt lgkmcnt(14)
	v_mfma_f32_16x16x32_bf16 v[32:35], v[128:131], v[72:75], v[32:35]
	s_mov_b32 s29, s28
	ds_read_b64_tr_b16 v[180:181], v239 offset:28672
	ds_read_b64_tr_b16 v[182:183], v239 offset:29696
	v_exp_f32_e32 v174, v174
	v_mfma_f32_16x16x32_bf16 v[36:39], v[128:131], v[100:103], v[36:39]
	v_mov_b64_e32 v[130:131], s[30:31]
	v_mov_b64_e32 v[128:129], s[28:29]
	v_exp_f32_e32 v175, v175
	s_nop 0
	v_mfma_f32_16x16x32_bf16 v[108:111], v[128:131], v[72:75], v[108:111]
	v_mfma_f32_16x16x32_bf16 v[92:95], v[128:131], v[100:103], v[92:95]
	s_waitcnt lgkmcnt(14)
	v_mfma_f32_16x16x32_bf16 v[120:123], v[156:159], v[56:59], v[120:123]
	v_exp_f32_e32 v100, v160
	v_exp_f32_e32 v101, v161
	v_cvt_pk_bf16_f32 v72, v188, v189
	v_mfma_f32_16x16x32_bf16 v[124:127], v[156:159], v[80:83], v[124:127]
	v_cvt_pk_bf16_f32 v73, v190, v191
	v_cvt_pk_bf16_f32 v74, v184, v185
	v_cvt_pk_bf16_f32 v75, v186, v187
	s_waitcnt lgkmcnt(12)
	v_mfma_f32_16x16x32_bf16 v[112:115], v[152:155], v[56:59], v[112:115]
	v_exp_f32_e32 v102, v162
	v_exp_f32_e32 v103, v163
	v_mfma_f32_16x16x32_bf16 v[116:119], v[152:155], v[80:83], v[116:119]
	s_waitcnt lgkmcnt(10)
	v_mfma_f32_16x16x32_bf16 v[96:99], v[148:151], v[56:59], v[96:99]
	v_exp_f32_e32 v152, v168
	v_exp_f32_e32 v153, v169
	v_mfma_f32_16x16x32_bf16 v[104:107], v[148:151], v[80:83], v[104:107]
	s_waitcnt lgkmcnt(8)
	v_mfma_f32_16x16x32_bf16 v[84:87], v[144:147], v[56:59], v[84:87]
	v_exp_f32_e32 v148, v170
	v_exp_f32_e32 v149, v171
	v_mfma_f32_16x16x32_bf16 v[88:91], v[144:147], v[80:83], v[88:91]
	s_waitcnt lgkmcnt(6)
	v_mfma_f32_16x16x32_bf16 v[68:71], v[140:143], v[56:59], v[68:71]
	v_cvt_pk_bf16_f32 v100, v100, v101
	v_cvt_pk_bf16_f32 v101, v102, v103
	v_cvt_pk_bf16_f32 v102, v152, v153
	v_mfma_f32_16x16x32_bf16 v[76:79], v[140:143], v[80:83], v[76:79]
	v_cvt_pk_bf16_f32 v103, v148, v149
	v_exp_f32_e32 v140, v164
	v_exp_f32_e32 v141, v165
	s_waitcnt lgkmcnt(4)
	v_mfma_f32_16x16x32_bf16 v[60:63], v[136:139], v[56:59], v[60:63]
	v_exp_f32_e32 v142, v166
	v_exp_f32_e32 v143, v167
	v_mfma_f32_16x16x32_bf16 v[64:67], v[136:139], v[80:83], v[64:67]
	s_waitcnt lgkmcnt(2)
	v_mfma_f32_16x16x32_bf16 v[48:51], v[132:135], v[56:59], v[48:51]
	v_exp_f32_e32 v136, v176
	v_exp_f32_e32 v137, v177
	v_mfma_f32_16x16x32_bf16 v[52:55], v[132:135], v[80:83], v[52:55]
	s_waitcnt lgkmcnt(0)
	v_mfma_f32_16x16x32_bf16 v[32:35], v[180:183], v[56:59], v[32:35]
	v_exp_f32_e32 v132, v178
	v_exp_f32_e32 v133, v179
	v_mfma_f32_16x16x32_bf16 v[36:39], v[180:183], v[80:83], v[36:39]
	v_mfma_f32_16x16x32_bf16 v[108:111], v[128:131], v[56:59], v[108:111]
	v_mfma_f32_16x16x32_bf16 v[92:95], v[128:131], v[80:83], v[92:95]
	s_waitcnt lgkmcnt(0)
	s_barrier
	v_cvt_pk_bf16_f32 v56, v194, v195
	v_cvt_pk_bf16_f32 v57, v196, v197
	v_cvt_pk_bf16_f32 v58, v172, v173
	v_cvt_pk_bf16_f32 v59, v174, v175
	v_cvt_pk_bf16_f32 v80, v140, v141
	v_cvt_pk_bf16_f32 v81, v142, v143
	v_cvt_pk_bf16_f32 v82, v136, v137
	v_cvt_pk_bf16_f32 v83, v132, v133
	s_cmp_lg_u32 s82, s8
	s_cbranch_scc0 .LBB0_139
	s_mov_b32 s1, s8
	s_branch .LBB0_147
